# second split barrier: da->LN0 becomes shard barrier + global da-done arrival, waited at the LN0->xq site; deferred global counts are requested together with the panel arrival
# speedup vs baseline: 1.0098x; 1.0098x over previous
.LBB0_226:
	s_getreg_b32 s0, hwreg(HW_REG_XCC_ID, 0, 4)
	s_and_b32 s9, s0, 15
	s_waitcnt vmcnt(0)
	s_waitcnt vmcnt(0)
	s_barrier
	s_and_saveexec_b64 s[0:1], s[52:53]
	v_readlane_b32 s24, v255, 22
	s_cbranch_execz .LBB0_278
	v_readlane_b32 s98, v253, 2
	v_readlane_b32 s99, v253, 3
	s_nop 0
	s_add_u32 s98, s98, 0x7c000
	s_addc_u32 s99, s99, 0
	s_and_b32 vcc_hi, s2, 7
	s_sub_u32 vcc_lo, 7, vcc_hi
	s_add_u32 vcc_lo, vcc_lo, s3
	s_lshr_b32 vcc_lo, vcc_lo, 3
	s_lshl_b32 vcc_hi, vcc_hi, 8
	s_add_u32 vcc_hi, vcc_hi, 0x8000
	s_cmp_lt_u32 s101, 8
	s_cselect_b32 m0, 0, 0x800
	s_add_u32 vcc_hi, vcc_hi, m0
	v_mov_b32_e32 v3, vcc_hi
	v_mov_b32_e32 v4, 1
	s_mov_b32 vcc_hi, vcc_lo
	s_waitcnt vmcnt(0) lgkmcnt(0)
	global_atomic_add v5, v3, v4, s[98:99] sc0
	s_waitcnt vmcnt(0)
	v_readfirstlane_b32 vcc_lo, v5
	s_add_i32 vcc_lo, vcc_lo, 1
	s_cmp_ge_u32 vcc_lo, vcc_hi
	s_cbranch_scc1 .Lb3_pok_1
	s_movk_i32 m0, 0x7fff

.LBB0_292:
	s_getreg_b32 s0, hwreg(HW_REG_XCC_ID, 0, 4)
	s_and_b32 s9, s0, 15
	s_waitcnt vmcnt(0)
	v_readlane_b32 s52, v253, 4
	v_readlane_b32 s53, v253, 5
	s_barrier
	s_and_saveexec_b64 s[0:1], s[52:53]
	v_readlane_b32 s54, v255, 8
	v_readlane_b32 s55, v255, 9
	s_cbranch_execz .LBB0_344
	v_readlane_b32 s98, v253, 2
	v_readlane_b32 s99, v253, 3
	s_nop 0
	s_add_u32 s98, s98, 0x7c000
	s_addc_u32 s99, s99, 0
	s_and_b32 vcc_hi, s2, 7
	s_sub_u32 vcc_lo, 7, vcc_hi
	s_add_u32 vcc_lo, vcc_lo, s3
	s_lshr_b32 vcc_lo, vcc_lo, 3
	s_lshl_b32 vcc_hi, vcc_hi, 8
	s_add_u32 vcc_hi, vcc_hi, 0x9000
	s_cmp_lt_u32 s101, 8
	s_cselect_b32 m0, 0, 0x800
	s_add_u32 vcc_hi, vcc_hi, m0
	v_mov_b32_e32 v3, vcc_hi
	v_mov_b32_e32 v4, 1
	s_mov_b32 vcc_hi, vcc_lo
	s_waitcnt vmcnt(0) lgkmcnt(0)
	global_atomic_add v5, v3, v4, s[98:99] sc0
	v_mov_b32_e32 v6, 0xa100
	global_atomic_add v6, v4, s[98:99]
	s_waitcnt vmcnt(0)
	v_readfirstlane_b32 vcc_lo, v5
	s_add_i32 vcc_lo, vcc_lo, 1
	s_cmp_ge_u32 vcc_lo, vcc_hi
	s_cbranch_scc1 .Lb3_pok_2
	s_movk_i32 m0, 0x7fff

.LBB0_866:
	s_getreg_b32 s0, hwreg(HW_REG_XCC_ID, 0, 4)
	s_and_b32 s10, s0, 15
	s_waitcnt vmcnt(0)
	s_waitcnt vmcnt(0)
	s_barrier
	s_and_saveexec_b64 s[0:1], s[52:53]
	v_readlane_b32 s14, v255, 14
	v_readlane_b32 s16, v255, 16
	v_readlane_b32 s15, v255, 15
	v_readlane_b32 s17, v255, 17
	s_add_i32 s101, s101, 1
	s_cbranch_execz .LBB0_918
	v_readlane_b32 s98, v253, 2
	v_readlane_b32 s99, v253, 3
	s_nop 0
	s_add_u32 s98, s98, 0x7c000
	s_addc_u32 s99, s99, 0
	s_and_b32 vcc_lo, s2, 63
	s_lshl_b32 vcc_lo, vcc_lo, 8
	s_add_u32 vcc_lo, vcc_lo, 0x2000
	v_mov_b32_e32 v3, vcc_lo
	v_mov_b32_e32 v4, 1
	s_lshl_b32 vcc_hi, s101, 2
	s_waitcnt vmcnt(0) lgkmcnt(0)
	global_atomic_add v5, v3, v4, s[98:99] sc0
	v_mov_b32_e32 v6, 0xa100
	global_load_dword v7, v6, s[98:99] sc1
	s_waitcnt vmcnt(0)
	v_readfirstlane_b32 vcc_lo, v5
	s_add_i32 vcc_lo, vcc_lo, 1
	s_cmp_ge_u32 vcc_lo, vcc_hi
	s_cbranch_scc1 .Lb3_pok_7
	s_movk_i32 m0, 0x7fff

.Lb3_pok_7:
	s_lshr_b32 vcc_hi, s101, 2
	s_add_i32 vcc_hi, vcc_hi, 1
	s_lshr_b32 vcc_hi, vcc_hi, 1
	s_mul_i32 vcc_hi, vcc_hi, s3
	v_readfirstlane_b32 vcc_lo, v7
	s_cmp_ge_u32 vcc_lo, vcc_hi
	s_cbranch_scc1 .Lb3_gok_7
	s_movk_i32 m0, 0x7fff

.LBB0_954:
	s_getreg_b32 s0, hwreg(HW_REG_XCC_ID, 0, 4)
	s_and_b32 s10, s0, 15
	s_waitcnt vmcnt(0)
	s_barrier
	s_and_saveexec_b64 s[0:1], s[52:53]
	v_readlane_b32 s28, v255, 14
	v_readlane_b32 s14, v255, 16
	v_readlane_b32 s29, v255, 15
	v_readlane_b32 s15, v255, 17
	s_add_i32 s101, s101, 1
	s_cbranch_execz .LBB0_1006
	v_readlane_b32 s98, v253, 2
	v_readlane_b32 s99, v253, 3
	s_nop 0
	s_add_u32 s98, s98, 0x7c000
	s_addc_u32 s99, s99, 0
	s_and_b32 vcc_lo, s2, 63
	s_lshl_b32 vcc_lo, vcc_lo, 8
	s_add_u32 vcc_lo, vcc_lo, 0x2000
	v_mov_b32_e32 v3, vcc_lo
	v_mov_b32_e32 v4, 1
	s_lshl_b32 vcc_hi, s101, 2
	s_waitcnt vmcnt(0) lgkmcnt(0)
	global_atomic_add v5, v3, v4, s[98:99] sc0
	v_mov_b32_e32 v6, 0xa000
	global_atomic_add v6, v4, s[98:99]
	s_waitcnt vmcnt(0)
	v_readfirstlane_b32 vcc_lo, v5
	s_add_i32 vcc_lo, vcc_lo, 1
	s_cmp_ge_u32 vcc_lo, vcc_hi
	s_cbranch_scc1 .Lb3_pok_8
	s_movk_i32 m0, 0x7fff

.LBB0_1067:
	s_getreg_b32 s0, hwreg(HW_REG_XCC_ID, 0, 4)
	s_and_b32 s10, s0, 15
	s_waitcnt vmcnt(0)
	s_barrier
	s_and_saveexec_b64 s[0:1], s[52:53]
	v_readlane_b32 s22, v255, 16
	v_readlane_b32 s23, v255, 17
	s_add_i32 s101, s101, 1
	s_cbranch_execz .LBB0_1119
	v_readlane_b32 s98, v253, 2
	v_readlane_b32 s99, v253, 3
	s_nop 0
	s_add_u32 s98, s98, 0x7c000
	s_addc_u32 s99, s99, 0
	s_and_b32 vcc_lo, s2, 63
	s_lshl_b32 vcc_lo, vcc_lo, 8
	s_add_u32 vcc_lo, vcc_lo, 0x2000
	v_mov_b32_e32 v3, vcc_lo
	v_mov_b32_e32 v4, 1
	s_lshl_b32 vcc_hi, s101, 2
	s_waitcnt vmcnt(0) lgkmcnt(0)
	global_atomic_add v5, v3, v4, s[98:99] sc0
	v_mov_b32_e32 v6, 0xa000
	global_load_dword v7, v6, s[98:99] sc1
	s_waitcnt vmcnt(0)
	v_readfirstlane_b32 vcc_lo, v5
	s_add_i32 vcc_lo, vcc_lo, 1
	s_cmp_ge_u32 vcc_lo, vcc_hi
	s_cbranch_scc1 .Lb3_pok_9
	s_movk_i32 m0, 0x7fff

.Lb3_pok_9:
	s_add_i32 vcc_hi, s101, 1
	s_lshr_b32 vcc_hi, vcc_hi, 2
	s_mul_i32 vcc_hi, vcc_hi, s3
	v_readfirstlane_b32 vcc_lo, v7
	s_cmp_ge_u32 vcc_lo, vcc_hi
	s_cbranch_scc1 .Lb3_gok_9
	s_movk_i32 m0, 0x7fff

.LBB0_1156:
	s_getreg_b32 s0, hwreg(HW_REG_XCC_ID, 0, 4)
	s_and_b32 s4, s0, 15
	s_waitcnt vmcnt(0)
	s_waitcnt vmcnt(0)
	s_barrier
	s_and_saveexec_b64 s[0:1], s[52:53]
	s_add_i32 s101, s101, 1
	s_cbranch_execz .LBB0_1208
	v_readlane_b32 s98, v253, 2
	v_readlane_b32 s99, v253, 3
	s_nop 0
	s_add_u32 s98, s98, 0x7c000
	s_addc_u32 s99, s99, 0
	s_and_b32 vcc_lo, s2, 63
	s_lshl_b32 vcc_lo, vcc_lo, 8
	s_add_u32 vcc_lo, vcc_lo, 0x2000
	v_mov_b32_e32 v3, vcc_lo
	v_mov_b32_e32 v4, 1
	s_lshl_b32 vcc_hi, s101, 2
	s_waitcnt vmcnt(0) lgkmcnt(0)
	global_atomic_add v5, v3, v4, s[98:99] sc0
	s_waitcnt vmcnt(0)
	v_readfirstlane_b32 vcc_lo, v5
	s_add_i32 vcc_lo, vcc_lo, 1
	s_cmp_ge_u32 vcc_lo, vcc_hi
	s_cbranch_scc1 .Lb3_pok_10
	s_movk_i32 m0, 0x7fff
